# P8 branch epilogue: gate and running-sum tiles prefetched in two batches of 4 rows (was one load+wait per group); P0 mem-KV transposes moved to waves with one gu1 item; MLA 2nd-block K fragment prefet
# speedup vs baseline: 1.0043x; 1.0043x over previous
;     if (nb1 < 0) nb1 = N / 32;
;     const int nblk = nb1 - nb0, nitems = (K / 64) * nblk;
;     for (int item = gw; item < nitems; item += ngw) {
;         const int kb = item / nblk, nb = nb0 + item % nblk, k0 = 64 * kb, n0 = 32 * nb;
;         float tv[32];
; #pragma unroll
;         for (int i = 0; i < 32; ++i) { const int kk = 2 * i + (lane >> 5); tv[i] = W[(size_t)(k0 + kk) * N + n0 + (lane & 31)]; }
; #pragma unroll
;         for (int i = 0; i < 32; ++i) { const int kk = 2 * i + (lane >> 5); float v = tv[i]; if (gk) v *= gk[k0 + kk]; scr[kk * 33 + (lane & 31)] = v; }
; __global__ void __launch_bounds__(512, 2) fwd_mega(Args args) {
;     ...
;         transpose_mat(args.in[20], 1024, 1024, nullptr, 0, wMKV, nullptr, scr, gw, ngw, lane);
.LBB0_53:
	v_readlane_b32 s2, v249, 54
	s_cmpk_lt_i32 s2, 0x200
	s_cselect_b64 s[10:11], -1, 0
	s_add_i32 s99, s2, 0x500
	s_and_b32 s99, s99, 0x7ff
	s_cmpk_eq_i32 s86, 0x100
	s_cselect_b32 s99, s99, s2
	s_cmpk_gt_i32 s99, 0x1ff
	v_readlane_b32 s3, v249, 55
	s_cbranch_scc1 .LBB0_56
	s_add_u32 s12, s8, 0x1d00000
	v_mov_b32_e32 v5, 0
	s_mov_b32 s2, s99
	s_addc_u32 s13, s9, 0
	v_lshl_add_u64 v[14:15], s[60:61], 0, v[4:5]
	s_lshl_b32 s14, s2, 5
	s_lshl_b32 s15, s88, 5
	v_mov_b32_e32 v3, v5
	v_mov_b32_e32 v7, v5
	v_mov_b32_e32 v9, v5
	v_mov_b32_e32 v11, v5
	v_mov_b32_e32 v13, v5
	v_add_u32_e32 v1, 0x400, v45
	v_add_u32_e32 v5, 0x800, v45
	v_add_u32_e32 v16, 0xc00, v45
	v_add_u32_e32 v17, 0x1000, v45
	v_add_u32_e32 v18, 0x1400, v45
	v_add_u32_e32 v19, 0x1800, v45
	v_add_u32_e32 v20, 0x1c00, v45
	s_mov_b32 s33, s2
	v_readlane_b32 s3, v249, 55

; DI unsigned pk2(float lo, float hi) { typedef float v2f __attribute__((ext_vector_type(2))); typedef __bf16 v2b __attribute__((ext_vector_type(2))); v2f v = {lo, hi}; v2b b = __builtin_convertvector(v, v2b); return __builtin_bit_cast(unsigned, b); }
; DI float bflo(unsigned w) { return __uint_as_float(w << 16); }
; DI float bfhi(unsigned w) { return __uint_as_float(w & 0xffff0000u); }
;     DI void operator()(const f32x4 (&acc)[2][2][4][2], const Unit& u, int wr, int wc, int fr, int fq) const {
;         const int br = u.pm >> 6, row0 = (u.pm & 63) * 256 + wr * 64 + fr, col0 = (u.pn & 3) * 256 + wc * 32 + 8 * fq;
;         const bf16_t* G = G0 + (size_t)br * (16u << 20);
; #pragma unroll
;         for (int ai = 0; ai < 2; ++ai)
; #pragma unroll
;             for (int m = 0; m < 4; ++m)
; #pragma unroll
;                 for (int bj = 0; bj < 2; ++bj) {
;                     const size_t off = (size_t)(row0 + ai * 128 + m * 16) * DM + col0 + bj * 128;
;                     const u32x4 g = *(const u32x4*)(G + off); const f32x4 a = acc[ai][bj][m][0], b = acc[ai][bj][m][1];
;                     float o[8] = {bflo(g.x) * a[0], bfhi(g.x) * a[1], bflo(g.y) * a[2], bfhi(g.y) * a[3], bflo(g.z) * b[0], bfhi(g.z) * b[1], bflo(g.w) * b[2], bfhi(g.w) * b[3]};
;                     if (br > 0) { const u32x4 p = *(const u32x4*)(MG + off); o[0] += bflo(p.x); o[1] += bfhi(p.x); o[2] += bflo(p.y); o[3] += bfhi(p.y); o[4] += bflo(p.z); o[5] += bfhi(p.z); o[6] += bflo(p.w); o[7] += bfhi(p.w); }
;                     u32x4 w; w.x = pk2(o[0], o[1]); w.y = pk2(o[2], o[3]); w.z = pk2(o[4], o[5]); w.w = pk2(o[6], o[7]); *(u32x4*)(MG + off) = w;
.LBB0_1630:
	s_lshl_b32 s5, s53, 8
	s_and_b32 s5, s5, 0x3f00
	v_add_u32_e32 v136, s5, v150
	s_lshl_b32 s5, s52, 8
	s_ashr_i32 s4, s53, 6
	s_and_b32 s5, s5, 0x300
	v_or_b32_e32 v156, s5, v152
	s_ashr_i32 s5, s4, 31
	s_lshl_b64 s[24:25], s[4:5], 25
	s_add_u32 s24, s42, s24
	v_lshlrev_b64 v[162:163], 10, v[136:137]
	s_addc_u32 s25, s43, s25
	v_or_b32_e32 v162, v162, v156
	v_lshl_add_u64 v[146:147], v[162:163], 1, s[24:25]
	s_nop 0
	v_lshlrev_b32_e32 v254, 1, v162
	v_mov_b32_e32 v251, 0
	v_mov_b32_e32 v250, v254
	v_lshl_add_u64 v[252:253], s[24:25], 0, v[250:251]
	global_load_dwordx4 v[168:171], v[252:253], off
	global_load_dwordx4 v[184:187], v[252:253], off offset:256
	v_add_u32_e32 v250, 0x8000, v254
	v_lshl_add_u64 v[252:253], s[24:25], 0, v[250:251]
	global_load_dwordx4 v[172:175], v[252:253], off
	global_load_dwordx4 v[188:191], v[252:253], off offset:256
	v_add_u32_e32 v250, 0x10000, v254
	v_lshl_add_u64 v[252:253], s[24:25], 0, v[250:251]
	global_load_dwordx4 v[176:179], v[252:253], off
	global_load_dwordx4 v[192:195], v[252:253], off offset:256
	v_add_u32_e32 v250, 0x18000, v254
	v_lshl_add_u64 v[252:253], s[24:25], 0, v[250:251]
	global_load_dwordx4 v[180:183], v[252:253], off
	global_load_dwordx4 v[198:201], v[252:253], off offset:256
	s_cmp_lt_i32 s4, 1
	s_cbranch_scc1 .Lp8_noA
	v_mov_b32_e32 v250, v254
	v_lshl_add_u64 v[252:253], s[28:29], 0, v[250:251]
	global_load_dwordx4 v[202:205], v[252:253], off
	global_load_dwordx4 v[218:221], v[252:253], off offset:256
	v_add_u32_e32 v250, 0x8000, v254
	v_lshl_add_u64 v[252:253], s[28:29], 0, v[250:251]
	global_load_dwordx4 v[206:209], v[252:253], off
	global_load_dwordx4 v[222:225], v[252:253], off offset:256
	v_add_u32_e32 v250, 0x10000, v254
	v_lshl_add_u64 v[252:253], s[28:29], 0, v[250:251]
	global_load_dwordx4 v[210:213], v[252:253], off
	global_load_dwordx4 v[226:229], v[252:253], off offset:256
	v_add_u32_e32 v250, 0x18000, v254
	v_lshl_add_u64 v[252:253], s[28:29], 0, v[250:251]
	global_load_dwordx4 v[214:217], v[252:253], off
	global_load_dwordx4 v[232:235], v[252:253], off offset:256
.Lp8_noA:
	s_cmp_gt_i32 s4, 0
	s_cselect_b64 s[26:27], -1, 0
	s_cmp_lt_i32 s4, 1
	s_waitcnt vmcnt(0)
	v_and_b32_e32 v149, 0xffff0000, v168
	v_lshlrev_b32_e32 v148, 16, v168
	v_and_b32_e32 v165, 0xffff0000, v169
	v_lshlrev_b32_e32 v164, 16, v169
	v_and_b32_e32 v159, 0xffff0000, v170
	v_lshlrev_b32_e32 v158, 16, v170
	v_and_b32_e32 v167, 0xffff0000, v171
	v_lshlrev_b32_e32 v166, 16, v171
	v_pk_mul_f32 v[148:149], v[124:125], v[148:149]
	v_pk_mul_f32 v[126:127], v[126:127], v[164:165]
	v_pk_mul_f32 v[124:125], v[120:121], v[158:159]
	v_pk_mul_f32 v[122:123], v[122:123], v[166:167]
	v_lshl_add_u64 v[120:121], v[162:163], 1, s[28:29]
	s_cbranch_scc1 .LBB0_1632
	s_nop 0
	v_and_b32_e32 v163, 0xffff0000, v202
	v_lshlrev_b32_e32 v162, 16, v202
	v_and_b32_e32 v165, 0xffff0000, v203
	v_lshlrev_b32_e32 v164, 16, v203
	v_and_b32_e32 v159, 0xffff0000, v204
	v_lshlrev_b32_e32 v158, 16, v204
	v_and_b32_e32 v167, 0xffff0000, v205
	v_lshlrev_b32_e32 v166, 16, v205
	v_pk_add_f32 v[148:149], v[148:149], v[162:163]
	v_pk_add_f32 v[126:127], v[126:127], v[164:165]
	v_pk_add_f32 v[124:125], v[124:125], v[158:159]
	v_pk_add_f32 v[122:123], v[122:123], v[166:167]
.LBB0_1632:
	v_cvt_pk_bf16_f32 v158, v148, v149
	v_cvt_pk_bf16_f32 v159, v126, v127
	v_cvt_pk_bf16_f32 v160, v124, v125
	v_cvt_pk_bf16_f32 v161, v122, v123
	global_store_dwordx4 v[120:121], v[158:161], off
	s_nop 0
	v_cndmask_b32_e64 v126, 0, 1, s[26:27]
	v_cmp_ne_u32_e64 s[4:5], 1, v126
	s_andn2_b64 vcc, exec, s[26:27]
	v_and_b32_e32 v127, 0xffff0000, v184
	v_lshlrev_b32_e32 v126, 16, v184
	v_and_b32_e32 v147, 0xffff0000, v185
	v_lshlrev_b32_e32 v146, 16, v185
	v_and_b32_e32 v149, 0xffff0000, v186
	v_lshlrev_b32_e32 v148, 16, v186
	v_and_b32_e32 v159, 0xffff0000, v187
	v_lshlrev_b32_e32 v158, 16, v187
	v_pk_mul_f32 v[122:123], v[116:117], v[126:127]
	v_pk_mul_f32 v[118:119], v[118:119], v[146:147]
	v_pk_mul_f32 v[116:117], v[112:113], v[148:149]
	v_pk_mul_f32 v[112:113], v[114:115], v[158:159]
	s_cbranch_vccnz .LBB0_1634
	s_nop 0
	v_and_b32_e32 v115, 0xffff0000, v218
	v_lshlrev_b32_e32 v114, 16, v218
	v_and_b32_e32 v147, 0xffff0000, v219
	v_lshlrev_b32_e32 v146, 16, v219
	v_and_b32_e32 v125, 0xffff0000, v220
	v_lshlrev_b32_e32 v124, 16, v220
	v_and_b32_e32 v149, 0xffff0000, v221
	v_lshlrev_b32_e32 v148, 16, v221
	v_pk_add_f32 v[122:123], v[122:123], v[114:115]
	v_pk_add_f32 v[118:119], v[118:119], v[146:147]
	v_pk_add_f32 v[116:117], v[116:117], v[124:125]
	v_pk_add_f32 v[112:113], v[112:113], v[148:149]
.LBB0_1634:
	v_cvt_pk_bf16_f32 v116, v116, v117
	v_cvt_pk_bf16_f32 v117, v112, v113
	v_or_b32_e32 v112, 16, v136
	v_mov_b32_e32 v113, v137
	v_cvt_pk_bf16_f32 v115, v118, v119
	v_lshlrev_b64 v[118:119], 10, v[112:113]
	v_cvt_pk_bf16_f32 v114, v122, v123
	v_or_b32_e32 v118, v118, v156
	global_store_dwordx4 v[120:121], v[114:117], off offset:256
	v_lshl_add_u64 v[112:113], v[118:119], 1, s[24:25]
	s_nop 0
	s_and_b64 vcc, exec, s[4:5]
	v_and_b32_e32 v121, 0xffff0000, v172
	v_lshlrev_b32_e32 v120, 16, v172
	v_and_b32_e32 v123, 0xffff0000, v173
	v_lshlrev_b32_e32 v122, 16, v173
	v_and_b32_e32 v125, 0xffff0000, v174
	v_lshlrev_b32_e32 v124, 16, v174
	v_and_b32_e32 v127, 0xffff0000, v175
	v_lshlrev_b32_e32 v126, 16, v175
	v_pk_mul_f32 v[114:115], v[108:109], v[120:121]
	v_pk_mul_f32 v[110:111], v[110:111], v[122:123]
	v_pk_mul_f32 v[108:109], v[104:105], v[124:125]
	v_pk_mul_f32 v[106:107], v[106:107], v[126:127]
	v_lshl_add_u64 v[104:105], v[118:119], 1, s[28:29]
	s_cbranch_vccnz .LBB0_1636
	s_nop 0
	v_and_b32_e32 v121, 0xffff0000, v206
	v_lshlrev_b32_e32 v120, 16, v206
	v_and_b32_e32 v123, 0xffff0000, v207
	v_lshlrev_b32_e32 v122, 16, v207
	v_and_b32_e32 v117, 0xffff0000, v208
	v_lshlrev_b32_e32 v116, 16, v208
	v_and_b32_e32 v125, 0xffff0000, v209
	v_lshlrev_b32_e32 v124, 16, v209
	v_pk_add_f32 v[114:115], v[114:115], v[120:121]
	v_pk_add_f32 v[110:111], v[110:111], v[122:123]
	v_pk_add_f32 v[108:109], v[108:109], v[116:117]
	v_pk_add_f32 v[106:107], v[106:107], v[124:125]
; DI unsigned pk2(float lo, float hi) { typedef float v2f __attribute__((ext_vector_type(2))); typedef __bf16 v2b __attribute__((ext_vector_type(2))); v2f v = {lo, hi}; v2b b = __builtin_convertvector(v, v2b); return __builtin_bit_cast(unsigned, b); }
; DI float bflo(unsigned w) { return __uint_as_float(w << 16); }
; DI float bfhi(unsigned w) { return __uint_as_float(w & 0xffff0000u); }
;     DI void operator()(const f32x4 (&acc)[2][2][4][2], const Unit& u, int wr, int wc, int fr, int fq) const {
;     ...
;                 for (int bj = 0; bj < 2; ++bj) {
;                     const size_t off = (size_t)(row0 + ai * 128 + m * 16) * DM + col0 + bj * 128;
;                     const u32x4 g = *(const u32x4*)(G + off); const f32x4 a = acc[ai][bj][m][0], b = acc[ai][bj][m][1];
;                     float o[8] = {bflo(g.x) * a[0], bfhi(g.x) * a[1], bflo(g.y) * a[2], bfhi(g.y) * a[3], bflo(g.z) * b[0], bfhi(g.z) * b[1], bflo(g.w) * b[2], bfhi(g.w) * b[3]};
;                     if (br > 0) { const u32x4 p = *(const u32x4*)(MG + off); o[0] += bflo(p.x); o[1] += bfhi(p.x); o[2] += bflo(p.y); o[3] += bfhi(p.y); o[4] += bflo(p.z); o[5] += bfhi(p.z); o[6] += bflo(p.w); o[7] += bfhi(p.w); }
;                     u32x4 w; w.x = pk2(o[0], o[1]); w.y = pk2(o[2], o[3]); w.z = pk2(o[4], o[5]); w.w = pk2(o[6], o[7]); *(u32x4*)(MG + off) = w;
.LBB0_1636:
	v_cvt_pk_bf16_f32 v114, v114, v115
	v_cvt_pk_bf16_f32 v115, v110, v111
	v_cvt_pk_bf16_f32 v116, v108, v109
	v_cvt_pk_bf16_f32 v117, v106, v107
	global_store_dwordx4 v[104:105], v[114:117], off
	s_nop 0
	s_and_b64 vcc, exec, s[4:5]
	v_and_b32_e32 v111, 0xffff0000, v188
	v_lshlrev_b32_e32 v110, 16, v188
	v_and_b32_e32 v113, 0xffff0000, v189
	v_lshlrev_b32_e32 v112, 16, v189
	v_and_b32_e32 v115, 0xffff0000, v190
	v_lshlrev_b32_e32 v114, 16, v190
	v_and_b32_e32 v117, 0xffff0000, v191
	v_lshlrev_b32_e32 v116, 16, v191
	v_pk_mul_f32 v[106:107], v[100:101], v[110:111]
	v_pk_mul_f32 v[102:103], v[102:103], v[112:113]
	v_pk_mul_f32 v[100:101], v[96:97], v[114:115]
	v_pk_mul_f32 v[96:97], v[98:99], v[116:117]
	s_cbranch_vccnz .LBB0_1638
	s_nop 0
	v_and_b32_e32 v99, 0xffff0000, v222
	v_lshlrev_b32_e32 v98, 16, v222
	v_and_b32_e32 v113, 0xffff0000, v223
	v_lshlrev_b32_e32 v112, 16, v223
	v_and_b32_e32 v109, 0xffff0000, v224
	v_lshlrev_b32_e32 v108, 16, v224
	v_and_b32_e32 v115, 0xffff0000, v225
	v_lshlrev_b32_e32 v114, 16, v225
	v_pk_add_f32 v[106:107], v[106:107], v[98:99]
	v_pk_add_f32 v[102:103], v[102:103], v[112:113]
	v_pk_add_f32 v[100:101], v[100:101], v[108:109]
	v_pk_add_f32 v[96:97], v[96:97], v[114:115]
.LBB0_1638:
	v_cvt_pk_bf16_f32 v100, v100, v101
	v_cvt_pk_bf16_f32 v101, v96, v97
	v_or_b32_e32 v96, 32, v136
	v_mov_b32_e32 v97, v137
	v_cvt_pk_bf16_f32 v99, v102, v103
	v_lshlrev_b64 v[102:103], 10, v[96:97]
	v_cvt_pk_bf16_f32 v98, v106, v107
	v_or_b32_e32 v102, v102, v156
	global_store_dwordx4 v[104:105], v[98:101], off offset:256
	v_lshl_add_u64 v[96:97], v[102:103], 1, s[24:25]
	s_nop 0
	s_and_b64 vcc, exec, s[4:5]
	v_and_b32_e32 v105, 0xffff0000, v176
	v_lshlrev_b32_e32 v104, 16, v176
	v_and_b32_e32 v107, 0xffff0000, v177
	v_lshlrev_b32_e32 v106, 16, v177
	v_and_b32_e32 v109, 0xffff0000, v178
	v_lshlrev_b32_e32 v108, 16, v178
	v_and_b32_e32 v111, 0xffff0000, v179
	v_lshlrev_b32_e32 v110, 16, v179
	v_pk_mul_f32 v[98:99], v[92:93], v[104:105]
	v_pk_mul_f32 v[94:95], v[94:95], v[106:107]
	v_pk_mul_f32 v[92:93], v[88:89], v[108:109]
	v_pk_mul_f32 v[90:91], v[90:91], v[110:111]
	v_lshl_add_u64 v[88:89], v[102:103], 1, s[28:29]
	s_cbranch_vccnz .LBB0_1640
	s_nop 0
	v_and_b32_e32 v105, 0xffff0000, v210
	v_lshlrev_b32_e32 v104, 16, v210
	v_and_b32_e32 v107, 0xffff0000, v211
	v_lshlrev_b32_e32 v106, 16, v211
	v_and_b32_e32 v101, 0xffff0000, v212
	v_lshlrev_b32_e32 v100, 16, v212
	v_and_b32_e32 v109, 0xffff0000, v213
	v_lshlrev_b32_e32 v108, 16, v213
	v_pk_add_f32 v[98:99], v[98:99], v[104:105]
	v_pk_add_f32 v[94:95], v[94:95], v[106:107]
	v_pk_add_f32 v[92:93], v[92:93], v[100:101]
	v_pk_add_f32 v[90:91], v[90:91], v[108:109]
.LBB0_1640:
	v_cvt_pk_bf16_f32 v98, v98, v99
	v_cvt_pk_bf16_f32 v99, v94, v95
	v_cvt_pk_bf16_f32 v100, v92, v93
	v_cvt_pk_bf16_f32 v101, v90, v91
	global_store_dwordx4 v[88:89], v[98:101], off
	s_nop 0
	s_and_b64 vcc, exec, s[4:5]
	v_and_b32_e32 v95, 0xffff0000, v192
	v_lshlrev_b32_e32 v94, 16, v192
	v_and_b32_e32 v97, 0xffff0000, v193
	v_lshlrev_b32_e32 v96, 16, v193
	v_and_b32_e32 v99, 0xffff0000, v194
	v_lshlrev_b32_e32 v98, 16, v194
	v_and_b32_e32 v101, 0xffff0000, v195
	v_lshlrev_b32_e32 v100, 16, v195
	v_pk_mul_f32 v[90:91], v[84:85], v[94:95]
	v_pk_mul_f32 v[86:87], v[86:87], v[96:97]
	v_pk_mul_f32 v[84:85], v[80:81], v[98:99]
	v_pk_mul_f32 v[80:81], v[82:83], v[100:101]
	s_cbranch_vccnz .LBB0_1642
	s_nop 0
	v_and_b32_e32 v83, 0xffff0000, v226
	v_lshlrev_b32_e32 v82, 16, v226
	v_and_b32_e32 v97, 0xffff0000, v227
	v_lshlrev_b32_e32 v96, 16, v227
	v_and_b32_e32 v93, 0xffff0000, v228
	v_lshlrev_b32_e32 v92, 16, v228
	v_and_b32_e32 v99, 0xffff0000, v229
	v_lshlrev_b32_e32 v98, 16, v229
	v_pk_add_f32 v[90:91], v[90:91], v[82:83]
	v_pk_add_f32 v[86:87], v[86:87], v[96:97]
	v_pk_add_f32 v[84:85], v[84:85], v[92:93]
	v_pk_add_f32 v[80:81], v[80:81], v[98:99]
.LBB0_1642:
	v_cvt_pk_bf16_f32 v84, v84, v85
	v_cvt_pk_bf16_f32 v85, v80, v81
	v_or_b32_e32 v80, 48, v136
	v_mov_b32_e32 v81, v137
	v_cvt_pk_bf16_f32 v83, v86, v87
	v_lshlrev_b64 v[86:87], 10, v[80:81]
	v_cvt_pk_bf16_f32 v82, v90, v91
	v_or_b32_e32 v86, v86, v156
	global_store_dwordx4 v[88:89], v[82:85], off offset:256
	v_lshl_add_u64 v[80:81], v[86:87], 1, s[24:25]
	s_nop 0
	s_and_b64 vcc, exec, s[4:5]
	v_and_b32_e32 v89, 0xffff0000, v180
	v_lshlrev_b32_e32 v88, 16, v180
	v_and_b32_e32 v91, 0xffff0000, v181
	v_lshlrev_b32_e32 v90, 16, v181
	v_and_b32_e32 v93, 0xffff0000, v182
	v_lshlrev_b32_e32 v92, 16, v182
	v_and_b32_e32 v95, 0xffff0000, v183
	v_lshlrev_b32_e32 v94, 16, v183
	v_pk_mul_f32 v[82:83], v[76:77], v[88:89]
	v_pk_mul_f32 v[78:79], v[78:79], v[90:91]
	v_pk_mul_f32 v[76:77], v[72:73], v[92:93]
	v_pk_mul_f32 v[74:75], v[74:75], v[94:95]
	v_lshl_add_u64 v[72:73], v[86:87], 1, s[28:29]
	s_cbranch_vccnz .LBB0_1644
	s_nop 0
	v_and_b32_e32 v89, 0xffff0000, v214
	v_lshlrev_b32_e32 v88, 16, v214
	v_and_b32_e32 v91, 0xffff0000, v215
	v_lshlrev_b32_e32 v90, 16, v215
	v_and_b32_e32 v85, 0xffff0000, v216
	v_lshlrev_b32_e32 v84, 16, v216
	v_and_b32_e32 v93, 0xffff0000, v217
	v_lshlrev_b32_e32 v92, 16, v217
	v_pk_add_f32 v[82:83], v[82:83], v[88:89]
	v_pk_add_f32 v[78:79], v[78:79], v[90:91]
	v_pk_add_f32 v[76:77], v[76:77], v[84:85]
	v_pk_add_f32 v[74:75], v[74:75], v[92:93]
; DI unsigned pk2(float lo, float hi) { typedef float v2f __attribute__((ext_vector_type(2))); typedef __bf16 v2b __attribute__((ext_vector_type(2))); v2f v = {lo, hi}; v2b b = __builtin_convertvector(v, v2b); return __builtin_bit_cast(unsigned, b); }
; DI float bflo(unsigned w) { return __uint_as_float(w << 16); }
; DI float bfhi(unsigned w) { return __uint_as_float(w & 0xffff0000u); }
;     DI void operator()(const f32x4 (&acc)[2][2][4][2], const Unit& u, int wr, int wc, int fr, int fq) const {
;     ...
;                 for (int bj = 0; bj < 2; ++bj) {
;                     const size_t off = (size_t)(row0 + ai * 128 + m * 16) * DM + col0 + bj * 128;
;                     const u32x4 g = *(const u32x4*)(G + off); const f32x4 a = acc[ai][bj][m][0], b = acc[ai][bj][m][1];
;                     float o[8] = {bflo(g.x) * a[0], bfhi(g.x) * a[1], bflo(g.y) * a[2], bfhi(g.y) * a[3], bflo(g.z) * b[0], bfhi(g.z) * b[1], bflo(g.w) * b[2], bfhi(g.w) * b[3]};
;                     if (br > 0) { const u32x4 p = *(const u32x4*)(MG + off); o[0] += bflo(p.x); o[1] += bfhi(p.x); o[2] += bflo(p.y); o[3] += bfhi(p.y); o[4] += bflo(p.z); o[5] += bfhi(p.z); o[6] += bflo(p.w); o[7] += bfhi(p.w); }
;                     u32x4 w; w.x = pk2(o[0], o[1]); w.y = pk2(o[2], o[3]); w.z = pk2(o[4], o[5]); w.w = pk2(o[6], o[7]); *(u32x4*)(MG + off) = w;
.LBB0_1644:
	v_cvt_pk_bf16_f32 v82, v82, v83
	v_cvt_pk_bf16_f32 v83, v78, v79
	v_cvt_pk_bf16_f32 v84, v76, v77
	v_cvt_pk_bf16_f32 v85, v74, v75
	global_store_dwordx4 v[72:73], v[82:85], off
	s_nop 0
	s_and_b64 vcc, exec, s[4:5]
	v_and_b32_e32 v79, 0xffff0000, v198
	v_lshlrev_b32_e32 v78, 16, v198
	v_and_b32_e32 v81, 0xffff0000, v199
	v_lshlrev_b32_e32 v80, 16, v199
	v_and_b32_e32 v83, 0xffff0000, v200
	v_lshlrev_b32_e32 v82, 16, v200
	v_and_b32_e32 v85, 0xffff0000, v201
	v_lshlrev_b32_e32 v84, 16, v201
	v_pk_mul_f32 v[74:75], v[68:69], v[78:79]
	v_pk_mul_f32 v[70:71], v[70:71], v[80:81]
	v_pk_mul_f32 v[68:69], v[64:65], v[82:83]
	v_pk_mul_f32 v[64:65], v[66:67], v[84:85]
	s_cbranch_vccnz .LBB0_1646
	s_nop 0
	v_and_b32_e32 v67, 0xffff0000, v232
	v_lshlrev_b32_e32 v66, 16, v232
	v_and_b32_e32 v81, 0xffff0000, v233
	v_lshlrev_b32_e32 v80, 16, v233
	v_and_b32_e32 v77, 0xffff0000, v234
	v_lshlrev_b32_e32 v76, 16, v234
	v_and_b32_e32 v83, 0xffff0000, v235
	v_lshlrev_b32_e32 v82, 16, v235
	v_pk_add_f32 v[74:75], v[74:75], v[66:67]
	v_pk_add_f32 v[70:71], v[70:71], v[80:81]
	v_pk_add_f32 v[68:69], v[68:69], v[76:77]
	v_pk_add_f32 v[64:65], v[64:65], v[82:83]
.LBB0_1646:
	v_add_u32_e32 v250, 0x40000, v254
	v_lshl_add_u64 v[252:253], s[24:25], 0, v[250:251]
	global_load_dwordx4 v[168:171], v[252:253], off
	global_load_dwordx4 v[184:187], v[252:253], off offset:256
	v_add_u32_e32 v250, 0x48000, v254
	v_lshl_add_u64 v[252:253], s[24:25], 0, v[250:251]
	global_load_dwordx4 v[172:175], v[252:253], off
	global_load_dwordx4 v[188:191], v[252:253], off offset:256
	v_add_u32_e32 v250, 0x50000, v254
	v_lshl_add_u64 v[252:253], s[24:25], 0, v[250:251]
	global_load_dwordx4 v[176:179], v[252:253], off
	global_load_dwordx4 v[192:195], v[252:253], off offset:256
	v_add_u32_e32 v250, 0x58000, v254
	v_lshl_add_u64 v[252:253], s[24:25], 0, v[250:251]
	global_load_dwordx4 v[180:183], v[252:253], off
	global_load_dwordx4 v[198:201], v[252:253], off offset:256
	s_and_b64 vcc, exec, s[4:5]
	s_cbranch_vccnz .Lp8_noB
	v_add_u32_e32 v250, 0x40000, v254
	v_lshl_add_u64 v[252:253], s[28:29], 0, v[250:251]
	global_load_dwordx4 v[202:205], v[252:253], off
	global_load_dwordx4 v[218:221], v[252:253], off offset:256
	v_add_u32_e32 v250, 0x48000, v254
	v_lshl_add_u64 v[252:253], s[28:29], 0, v[250:251]
	global_load_dwordx4 v[206:209], v[252:253], off
	global_load_dwordx4 v[222:225], v[252:253], off offset:256
	v_add_u32_e32 v250, 0x50000, v254
	v_lshl_add_u64 v[252:253], s[28:29], 0, v[250:251]
	global_load_dwordx4 v[210:213], v[252:253], off
	global_load_dwordx4 v[226:229], v[252:253], off offset:256
	v_add_u32_e32 v250, 0x58000, v254
	v_lshl_add_u64 v[252:253], s[28:29], 0, v[250:251]
	global_load_dwordx4 v[214:217], v[252:253], off
	global_load_dwordx4 v[232:235], v[252:253], off offset:256
.Lp8_noB:
	v_cvt_pk_bf16_f32 v68, v68, v69
	v_cvt_pk_bf16_f32 v69, v64, v65
	v_add_u32_e32 v64, 0x80, v136
	v_mov_b32_e32 v65, v137
	v_cvt_pk_bf16_f32 v67, v70, v71
	v_lshlrev_b64 v[70:71], 10, v[64:65]
	v_cvt_pk_bf16_f32 v66, v74, v75
	v_or_b32_e32 v70, v70, v156
	global_store_dwordx4 v[72:73], v[66:69], off offset:256
	v_lshl_add_u64 v[64:65], v[70:71], 1, s[24:25]
	s_nop 0
	s_and_b64 vcc, exec, s[4:5]
	s_waitcnt vmcnt(1)
	v_and_b32_e32 v73, 0xffff0000, v168
	v_lshlrev_b32_e32 v72, 16, v168
	v_and_b32_e32 v75, 0xffff0000, v169
	v_lshlrev_b32_e32 v74, 16, v169
	v_and_b32_e32 v77, 0xffff0000, v170
	v_lshlrev_b32_e32 v76, 16, v170
	v_and_b32_e32 v79, 0xffff0000, v171
	v_lshlrev_b32_e32 v78, 16, v171
	v_pk_mul_f32 v[66:67], v[60:61], v[72:73]
	v_pk_mul_f32 v[62:63], v[62:63], v[74:75]
	v_pk_mul_f32 v[60:61], v[56:57], v[76:77]
	v_pk_mul_f32 v[58:59], v[58:59], v[78:79]
	v_lshl_add_u64 v[56:57], v[70:71], 1, s[28:29]
	s_cbranch_vccnz .LBB0_1648
	s_nop 0
	v_and_b32_e32 v73, 0xffff0000, v202
	v_lshlrev_b32_e32 v72, 16, v202
	v_and_b32_e32 v75, 0xffff0000, v203
	v_lshlrev_b32_e32 v74, 16, v203
	v_and_b32_e32 v69, 0xffff0000, v204
	v_lshlrev_b32_e32 v68, 16, v204
	v_and_b32_e32 v77, 0xffff0000, v205
	v_lshlrev_b32_e32 v76, 16, v205
	v_pk_add_f32 v[66:67], v[66:67], v[72:73]
	v_pk_add_f32 v[62:63], v[62:63], v[74:75]
	v_pk_add_f32 v[60:61], v[60:61], v[68:69]
	v_pk_add_f32 v[58:59], v[58:59], v[76:77]
.LBB0_1648:
	v_cvt_pk_bf16_f32 v66, v66, v67
	v_cvt_pk_bf16_f32 v67, v62, v63
	v_cvt_pk_bf16_f32 v68, v60, v61
	v_cvt_pk_bf16_f32 v69, v58, v59
	global_store_dwordx4 v[56:57], v[66:69], off
	s_nop 0
	s_and_b64 vcc, exec, s[4:5]
	v_and_b32_e32 v63, 0xffff0000, v184
	v_lshlrev_b32_e32 v62, 16, v184
	v_and_b32_e32 v65, 0xffff0000, v185
	v_lshlrev_b32_e32 v64, 16, v185
	v_and_b32_e32 v67, 0xffff0000, v186
	v_lshlrev_b32_e32 v66, 16, v186
	v_and_b32_e32 v69, 0xffff0000, v187
	v_lshlrev_b32_e32 v68, 16, v187
	v_pk_mul_f32 v[58:59], v[52:53], v[62:63]
	v_pk_mul_f32 v[54:55], v[54:55], v[64:65]
	v_pk_mul_f32 v[52:53], v[48:49], v[66:67]
	v_pk_mul_f32 v[48:49], v[50:51], v[68:69]
	s_cbranch_vccnz .LBB0_1650
	s_nop 0
	v_and_b32_e32 v51, 0xffff0000, v218
	v_lshlrev_b32_e32 v50, 16, v218
	v_and_b32_e32 v65, 0xffff0000, v219
	v_lshlrev_b32_e32 v64, 16, v219
	v_and_b32_e32 v61, 0xffff0000, v220
	v_lshlrev_b32_e32 v60, 16, v220
	v_and_b32_e32 v67, 0xffff0000, v221
	v_lshlrev_b32_e32 v66, 16, v221
	v_pk_add_f32 v[58:59], v[58:59], v[50:51]
	v_pk_add_f32 v[54:55], v[54:55], v[64:65]
	v_pk_add_f32 v[52:53], v[52:53], v[60:61]
	v_pk_add_f32 v[48:49], v[48:49], v[66:67]
; DI unsigned pk2(float lo, float hi) { typedef float v2f __attribute__((ext_vector_type(2))); typedef __bf16 v2b __attribute__((ext_vector_type(2))); v2f v = {lo, hi}; v2b b = __builtin_convertvector(v, v2b); return __builtin_bit_cast(unsigned, b); }
; DI float bflo(unsigned w) { return __uint_as_float(w << 16); }
; DI float bfhi(unsigned w) { return __uint_as_float(w & 0xffff0000u); }
;     DI void operator()(const f32x4 (&acc)[2][2][4][2], const Unit& u, int wr, int wc, int fr, int fq) const {
;     ...
;                 for (int bj = 0; bj < 2; ++bj) {
;                     const size_t off = (size_t)(row0 + ai * 128 + m * 16) * DM + col0 + bj * 128;
;                     const u32x4 g = *(const u32x4*)(G + off); const f32x4 a = acc[ai][bj][m][0], b = acc[ai][bj][m][1];
;                     float o[8] = {bflo(g.x) * a[0], bfhi(g.x) * a[1], bflo(g.y) * a[2], bfhi(g.y) * a[3], bflo(g.z) * b[0], bfhi(g.z) * b[1], bflo(g.w) * b[2], bfhi(g.w) * b[3]};
;                     if (br > 0) { const u32x4 p = *(const u32x4*)(MG + off); o[0] += bflo(p.x); o[1] += bfhi(p.x); o[2] += bflo(p.y); o[3] += bfhi(p.y); o[4] += bflo(p.z); o[5] += bfhi(p.z); o[6] += bflo(p.w); o[7] += bfhi(p.w); }
;                     u32x4 w; w.x = pk2(o[0], o[1]); w.y = pk2(o[2], o[3]); w.z = pk2(o[4], o[5]); w.w = pk2(o[6], o[7]); *(u32x4*)(MG + off) = w;
.LBB0_1650:
	v_cvt_pk_bf16_f32 v52, v52, v53
	v_cvt_pk_bf16_f32 v53, v48, v49
	v_add_u32_e32 v48, 0x90, v136
	v_mov_b32_e32 v49, v137
	v_cvt_pk_bf16_f32 v51, v54, v55
	v_lshlrev_b64 v[54:55], 10, v[48:49]
	v_cvt_pk_bf16_f32 v50, v58, v59
	v_or_b32_e32 v54, v54, v156
	global_store_dwordx4 v[56:57], v[50:53], off offset:256
	v_lshl_add_u64 v[48:49], v[54:55], 1, s[24:25]
	s_nop 0
	s_and_b64 vcc, exec, s[4:5]
	v_and_b32_e32 v57, 0xffff0000, v172
	v_lshlrev_b32_e32 v56, 16, v172
	v_and_b32_e32 v59, 0xffff0000, v173
	v_lshlrev_b32_e32 v58, 16, v173
	v_and_b32_e32 v61, 0xffff0000, v174
	v_lshlrev_b32_e32 v60, 16, v174
	v_and_b32_e32 v63, 0xffff0000, v175
	v_lshlrev_b32_e32 v62, 16, v175
	v_pk_mul_f32 v[50:51], v[44:45], v[56:57]
	v_pk_mul_f32 v[46:47], v[46:47], v[58:59]
	v_pk_mul_f32 v[44:45], v[40:41], v[60:61]
	v_pk_mul_f32 v[42:43], v[42:43], v[62:63]
	v_lshl_add_u64 v[40:41], v[54:55], 1, s[28:29]
	s_cbranch_vccnz .LBB0_1652
	s_nop 0
	v_and_b32_e32 v57, 0xffff0000, v206
	v_lshlrev_b32_e32 v56, 16, v206
	v_and_b32_e32 v59, 0xffff0000, v207
	v_lshlrev_b32_e32 v58, 16, v207
	v_and_b32_e32 v53, 0xffff0000, v208
	v_lshlrev_b32_e32 v52, 16, v208
	v_and_b32_e32 v61, 0xffff0000, v209
	v_lshlrev_b32_e32 v60, 16, v209
	v_pk_add_f32 v[50:51], v[50:51], v[56:57]
	v_pk_add_f32 v[46:47], v[46:47], v[58:59]
	v_pk_add_f32 v[44:45], v[44:45], v[52:53]
	v_pk_add_f32 v[42:43], v[42:43], v[60:61]
.LBB0_1652:
	v_cvt_pk_bf16_f32 v50, v50, v51
	v_cvt_pk_bf16_f32 v51, v46, v47
	v_cvt_pk_bf16_f32 v52, v44, v45
	v_cvt_pk_bf16_f32 v53, v42, v43
	global_store_dwordx4 v[40:41], v[50:53], off
	s_nop 0
	s_and_b64 vcc, exec, s[4:5]
	v_and_b32_e32 v47, 0xffff0000, v188
	v_lshlrev_b32_e32 v46, 16, v188
	v_and_b32_e32 v49, 0xffff0000, v189
	v_lshlrev_b32_e32 v48, 16, v189
	v_and_b32_e32 v51, 0xffff0000, v190
	v_lshlrev_b32_e32 v50, 16, v190
	v_and_b32_e32 v53, 0xffff0000, v191
	v_lshlrev_b32_e32 v52, 16, v191
	v_pk_mul_f32 v[42:43], v[36:37], v[46:47]
	v_pk_mul_f32 v[38:39], v[38:39], v[48:49]
	v_pk_mul_f32 v[36:37], v[32:33], v[50:51]
	v_pk_mul_f32 v[32:33], v[34:35], v[52:53]
	s_cbranch_vccnz .LBB0_1654
	s_nop 0
	v_and_b32_e32 v35, 0xffff0000, v222
	v_lshlrev_b32_e32 v34, 16, v222
	v_and_b32_e32 v49, 0xffff0000, v223
	v_lshlrev_b32_e32 v48, 16, v223
	v_and_b32_e32 v45, 0xffff0000, v224
	v_lshlrev_b32_e32 v44, 16, v224
	v_and_b32_e32 v51, 0xffff0000, v225
	v_lshlrev_b32_e32 v50, 16, v225
	v_pk_add_f32 v[42:43], v[42:43], v[34:35]
	v_pk_add_f32 v[38:39], v[38:39], v[48:49]
	v_pk_add_f32 v[36:37], v[36:37], v[44:45]
	v_pk_add_f32 v[32:33], v[32:33], v[50:51]
.LBB0_1654:
	v_cvt_pk_bf16_f32 v36, v36, v37
	v_cvt_pk_bf16_f32 v37, v32, v33
	v_add_u32_e32 v32, 0xa0, v136
	v_mov_b32_e32 v33, v137
	v_cvt_pk_bf16_f32 v35, v38, v39
	v_lshlrev_b64 v[38:39], 10, v[32:33]
	v_cvt_pk_bf16_f32 v34, v42, v43
	v_or_b32_e32 v38, v38, v156
	global_store_dwordx4 v[40:41], v[34:37], off offset:256
	v_lshl_add_u64 v[32:33], v[38:39], 1, s[24:25]
	s_nop 0
	s_and_b64 vcc, exec, s[4:5]
	v_and_b32_e32 v41, 0xffff0000, v176
	v_lshlrev_b32_e32 v40, 16, v176
	v_and_b32_e32 v43, 0xffff0000, v177
	v_lshlrev_b32_e32 v42, 16, v177
	v_and_b32_e32 v45, 0xffff0000, v178
	v_lshlrev_b32_e32 v44, 16, v178
	v_and_b32_e32 v47, 0xffff0000, v179
	v_lshlrev_b32_e32 v46, 16, v179
	v_pk_mul_f32 v[34:35], v[28:29], v[40:41]
	v_pk_mul_f32 v[30:31], v[30:31], v[42:43]
	v_pk_mul_f32 v[28:29], v[24:25], v[44:45]
	v_pk_mul_f32 v[26:27], v[26:27], v[46:47]
	v_lshl_add_u64 v[24:25], v[38:39], 1, s[28:29]
	s_cbranch_vccnz .LBB0_1656
	s_nop 0
	v_and_b32_e32 v41, 0xffff0000, v210
	v_lshlrev_b32_e32 v40, 16, v210
	v_and_b32_e32 v43, 0xffff0000, v211
	v_lshlrev_b32_e32 v42, 16, v211
	v_and_b32_e32 v37, 0xffff0000, v212
	v_lshlrev_b32_e32 v36, 16, v212
	v_and_b32_e32 v45, 0xffff0000, v213
	v_lshlrev_b32_e32 v44, 16, v213
	v_pk_add_f32 v[34:35], v[34:35], v[40:41]
	v_pk_add_f32 v[30:31], v[30:31], v[42:43]
	v_pk_add_f32 v[28:29], v[28:29], v[36:37]
	v_pk_add_f32 v[26:27], v[26:27], v[44:45]
; DI unsigned pk2(float lo, float hi) { typedef float v2f __attribute__((ext_vector_type(2))); typedef __bf16 v2b __attribute__((ext_vector_type(2))); v2f v = {lo, hi}; v2b b = __builtin_convertvector(v, v2b); return __builtin_bit_cast(unsigned, b); }
; DI float bflo(unsigned w) { return __uint_as_float(w << 16); }
; DI float bfhi(unsigned w) { return __uint_as_float(w & 0xffff0000u); }
;     DI void operator()(const f32x4 (&acc)[2][2][4][2], const Unit& u, int wr, int wc, int fr, int fq) const {
;     ...
;                 for (int bj = 0; bj < 2; ++bj) {
;                     const size_t off = (size_t)(row0 + ai * 128 + m * 16) * DM + col0 + bj * 128;
;                     const u32x4 g = *(const u32x4*)(G + off); const f32x4 a = acc[ai][bj][m][0], b = acc[ai][bj][m][1];
;                     float o[8] = {bflo(g.x) * a[0], bfhi(g.x) * a[1], bflo(g.y) * a[2], bfhi(g.y) * a[3], bflo(g.z) * b[0], bfhi(g.z) * b[1], bflo(g.w) * b[2], bfhi(g.w) * b[3]};
;                     if (br > 0) { const u32x4 p = *(const u32x4*)(MG + off); o[0] += bflo(p.x); o[1] += bfhi(p.x); o[2] += bflo(p.y); o[3] += bfhi(p.y); o[4] += bflo(p.z); o[5] += bfhi(p.z); o[6] += bflo(p.w); o[7] += bfhi(p.w); }
;                     u32x4 w; w.x = pk2(o[0], o[1]); w.y = pk2(o[2], o[3]); w.z = pk2(o[4], o[5]); w.w = pk2(o[6], o[7]); *(u32x4*)(MG + off) = w;
.LBB0_1656:
	v_cvt_pk_bf16_f32 v34, v34, v35
	v_cvt_pk_bf16_f32 v35, v30, v31
	v_cvt_pk_bf16_f32 v36, v28, v29
	v_cvt_pk_bf16_f32 v37, v26, v27
	global_store_dwordx4 v[24:25], v[34:37], off
	s_nop 0
	s_and_b64 vcc, exec, s[4:5]
	v_and_b32_e32 v31, 0xffff0000, v192
	v_lshlrev_b32_e32 v30, 16, v192
	v_and_b32_e32 v33, 0xffff0000, v193
	v_lshlrev_b32_e32 v32, 16, v193
	v_and_b32_e32 v35, 0xffff0000, v194
	v_lshlrev_b32_e32 v34, 16, v194
	v_and_b32_e32 v37, 0xffff0000, v195
	v_lshlrev_b32_e32 v36, 16, v195
	v_pk_mul_f32 v[26:27], v[20:21], v[30:31]
	v_pk_mul_f32 v[22:23], v[22:23], v[32:33]
	v_pk_mul_f32 v[20:21], v[16:17], v[34:35]
	v_pk_mul_f32 v[16:17], v[18:19], v[36:37]
	s_cbranch_vccnz .LBB0_1658
	s_nop 0
	v_and_b32_e32 v19, 0xffff0000, v226
	v_lshlrev_b32_e32 v18, 16, v226
	v_and_b32_e32 v33, 0xffff0000, v227
	v_lshlrev_b32_e32 v32, 16, v227
	v_and_b32_e32 v29, 0xffff0000, v228
	v_lshlrev_b32_e32 v28, 16, v228
	v_and_b32_e32 v35, 0xffff0000, v229
	v_lshlrev_b32_e32 v34, 16, v229
	v_pk_add_f32 v[26:27], v[26:27], v[18:19]
	v_pk_add_f32 v[22:23], v[22:23], v[32:33]
	v_pk_add_f32 v[20:21], v[20:21], v[28:29]
	v_pk_add_f32 v[16:17], v[16:17], v[34:35]
.LBB0_1658:
	v_add_u32_e32 v136, 0xb0, v136
	v_cvt_pk_bf16_f32 v19, v22, v23
	v_lshlrev_b64 v[22:23], 10, v[136:137]
	v_cvt_pk_bf16_f32 v18, v26, v27
	v_cvt_pk_bf16_f32 v20, v20, v21
	v_cvt_pk_bf16_f32 v21, v16, v17
	v_or_b32_e32 v22, v22, v156
	global_store_dwordx4 v[24:25], v[18:21], off offset:256
	v_lshl_add_u64 v[16:17], v[22:23], 1, s[24:25]
	s_nop 0
	s_and_b64 vcc, exec, s[4:5]
	v_and_b32_e32 v25, 0xffff0000, v180
	v_lshlrev_b32_e32 v24, 16, v180
	v_and_b32_e32 v27, 0xffff0000, v181
	v_lshlrev_b32_e32 v26, 16, v181
	v_and_b32_e32 v29, 0xffff0000, v182
	v_lshlrev_b32_e32 v28, 16, v182
	v_and_b32_e32 v31, 0xffff0000, v183
	v_lshlrev_b32_e32 v30, 16, v183
	v_pk_mul_f32 v[18:19], v[12:13], v[24:25]
	v_pk_mul_f32 v[14:15], v[14:15], v[26:27]
	v_pk_mul_f32 v[12:13], v[8:9], v[28:29]
	v_pk_mul_f32 v[10:11], v[10:11], v[30:31]
	v_lshl_add_u64 v[8:9], v[22:23], 1, s[28:29]
	s_cbranch_vccnz .LBB0_1660
	s_nop 0
	v_and_b32_e32 v25, 0xffff0000, v214
	v_lshlrev_b32_e32 v24, 16, v214
	v_and_b32_e32 v27, 0xffff0000, v215
	v_lshlrev_b32_e32 v26, 16, v215
	v_and_b32_e32 v21, 0xffff0000, v216
	v_lshlrev_b32_e32 v20, 16, v216
	v_and_b32_e32 v29, 0xffff0000, v217
	v_lshlrev_b32_e32 v28, 16, v217
	v_pk_add_f32 v[18:19], v[18:19], v[24:25]
	v_pk_add_f32 v[14:15], v[14:15], v[26:27]
	v_pk_add_f32 v[12:13], v[12:13], v[20:21]
	v_pk_add_f32 v[10:11], v[10:11], v[28:29]
.LBB0_1660:
	v_cvt_pk_bf16_f32 v18, v18, v19
	v_cvt_pk_bf16_f32 v19, v14, v15
	v_cvt_pk_bf16_f32 v20, v12, v13
	v_cvt_pk_bf16_f32 v21, v10, v11
	global_store_dwordx4 v[8:9], v[18:21], off
	s_nop 0
	s_and_b64 vcc, exec, s[4:5]
	v_and_b32_e32 v15, 0xffff0000, v198
	v_lshlrev_b32_e32 v14, 16, v198
	v_and_b32_e32 v17, 0xffff0000, v199
	v_lshlrev_b32_e32 v16, 16, v199
	v_and_b32_e32 v19, 0xffff0000, v200
	v_lshlrev_b32_e32 v18, 16, v200
	v_and_b32_e32 v21, 0xffff0000, v201
	v_lshlrev_b32_e32 v20, 16, v201
	v_pk_mul_f32 v[10:11], v[4:5], v[14:15]
	v_pk_mul_f32 v[6:7], v[6:7], v[16:17]
	v_pk_mul_f32 v[4:5], v[0:1], v[18:19]
	v_pk_mul_f32 v[0:1], v[2:3], v[20:21]
	s_cbranch_vccnz .LBB0_1662
	s_nop 0
	v_and_b32_e32 v3, 0xffff0000, v232
	v_lshlrev_b32_e32 v2, 16, v232
	v_and_b32_e32 v17, 0xffff0000, v233
	v_lshlrev_b32_e32 v16, 16, v233
	v_and_b32_e32 v13, 0xffff0000, v234
	v_lshlrev_b32_e32 v12, 16, v234
	v_and_b32_e32 v19, 0xffff0000, v235
	v_lshlrev_b32_e32 v18, 16, v235
	v_pk_add_f32 v[10:11], v[10:11], v[2:3]
	v_pk_add_f32 v[6:7], v[6:7], v[16:17]
	v_pk_add_f32 v[4:5], v[4:5], v[12:13]
	v_pk_add_f32 v[0:1], v[0:1], v[18:19]

; __global__ void __launch_bounds__(512, 2) fwd_mega(Args args) {
	.amdhsa_kernel _Z8fwd_mega4Args
		.amdhsa_group_segment_fixed_size 0
		.amdhsa_private_segment_fixed_size 0
		.amdhsa_kernarg_size 520
		.amdhsa_user_sgpr_count 2
		.amdhsa_user_sgpr_dispatch_ptr 0
		.amdhsa_user_sgpr_queue_ptr 0
		.amdhsa_user_sgpr_kernarg_segment_ptr 1
		.amdhsa_user_sgpr_dispatch_id 0
		.amdhsa_user_sgpr_kernarg_preload_length 0
		.amdhsa_user_sgpr_kernarg_preload_offset 0
		.amdhsa_user_sgpr_private_segment_size 0
		.amdhsa_uses_dynamic_stack 0
		.amdhsa_enable_private_segment 0
		.amdhsa_system_sgpr_workgroup_id_x 1
		.amdhsa_system_sgpr_workgroup_id_y 0
		.amdhsa_system_sgpr_workgroup_id_z 0
		.amdhsa_system_sgpr_workgroup_info 0
		.amdhsa_system_vgpr_workitem_id 2
		.amdhsa_next_free_vgpr 256
		.amdhsa_next_free_sgpr 101
		.amdhsa_accum_offset 256
		.amdhsa_reserve_vcc 1
		.amdhsa_float_round_mode_32 0
		.amdhsa_float_round_mode_16_64 0
		.amdhsa_float_denorm_mode_32 3
		.amdhsa_float_denorm_mode_16_64 3
		.amdhsa_dx10_clamp 1
		.amdhsa_ieee_mode 1
		.amdhsa_fp16_overflow 0
		.amdhsa_tg_split 0
		.amdhsa_exception_fp_ieee_invalid_op 0
		.amdhsa_exception_fp_denorm_src 0
		.amdhsa_exception_fp_ieee_div_zero 0
		.amdhsa_exception_fp_ieee_overflow 0
		.amdhsa_exception_fp_ieee_underflow 0
		.amdhsa_exception_fp_ieee_inexact 0
		.amdhsa_exception_int_div_zero 0
	.end_amdhsa_kernel

; __global__ void __launch_bounds__(512, 2) fwd_mega(Args args) {
amdhsa.kernels:
  - .agpr_count:     0
    .args:
      - .offset:         0
        .size:           264
        .value_kind:     by_value
      - .offset:         264
        .size:           4
        .value_kind:     hidden_block_count_x
      - .offset:         268
        .size:           4
        .value_kind:     hidden_block_count_y
      - .offset:         272
        .size:           4
        .value_kind:     hidden_block_count_z
      - .offset:         276
        .size:           2
        .value_kind:     hidden_group_size_x
      - .offset:         278
        .size:           2
        .value_kind:     hidden_group_size_y
      - .offset:         280
        .size:           2
        .value_kind:     hidden_group_size_z
      - .offset:         282
        .size:           2
        .value_kind:     hidden_remainder_x
      - .offset:         284
        .size:           2
        .value_kind:     hidden_remainder_y
      - .offset:         286
        .size:           2
        .value_kind:     hidden_remainder_z
      - .offset:         304
        .size:           8
        .value_kind:     hidden_global_offset_x
      - .offset:         312
        .size:           8
        .value_kind:     hidden_global_offset_y
      - .offset:         320
        .size:           8
        .value_kind:     hidden_global_offset_z
      - .offset:         328
        .size:           2
        .value_kind:     hidden_grid_dims
      - .offset:         352
        .size:           8
        .value_kind:     hidden_multigrid_sync_arg
      - .offset:         384
        .size:           4
        .value_kind:     hidden_dynamic_lds_size
    .group_segment_fixed_size: 0
    .kernarg_segment_align: 8
    .kernarg_segment_size: 520
    .language:       OpenCL C
    .language_version:
      - 2
      - 0
    .max_flat_workgroup_size: 512
    .name:           _Z8fwd_mega4Args
    .private_segment_fixed_size: 0
    .sgpr_count:     107
    .sgpr_spill_count: 88
    .symbol:         _Z8fwd_mega4Args.kd
    .uniform_work_group_size: 1
    .uses_dynamic_stack: false
    .vgpr_count:     256
    .vgpr_spill_count: 0
    .wavefront_size: 64
